# FFN tile-edge fix-up loop: the six HALO loads per item issued together with one wait (was one full wait per exec-masked load)
# baseline (speedup 1.0000x reference)
; __device__ __forceinline__ void ffn_edge_fix(const float* __restrict__ HALO, bf16_t* __restrict__ ACT, const float* __restrict__ cw, const float* __restrict__ cb, int pm, int tid) {
;     ...
;         const int which = it >= (FF / 4), c = 4 * (it - which * (FF / 4)), t = c >> 7, w = c & 127, col = 256 * t + w;
;         const float* hp; const float* hc; const float* hn; bool hasp = true, hasn = true;
;         if (!which) { hasp = (pm & 15) != 0; hp = HALO + (size_t)((pm - 1) * 4 + 3) * FF2; hc = HALO + (size_t)(pm * 4 + 0) * FF2; hn = HALO + (size_t)(pm * 4 + 1) * FF2; }
;         else { hasn = (pm & 15) != 15; hp = HALO + (size_t)(pm * 4 + 2) * FF2; hc = HALO + (size_t)(pm * 4 + 3) * FF2; hn = HALO + (size_t)((pm + 1) * 4 + 0) * FF2; }
;         const f32x4 z4 = (f32x4){0.f, 0.f, 0.f, 0.f};
;         const f32x4 pg = hasp ? *(const f32x4*)(hp + col) : z4, pv = hasp ? *(const f32x4*)(hp + col + 128) : z4;
;         const f32x4 cg_ = *(const f32x4*)(hc + col), cv_ = *(const f32x4*)(hc + col + 128);
;         const f32x4 ng = hasn ? *(const f32x4*)(hn + col) : z4, nv = hasn ? *(const f32x4*)(hn + col + 128) : z4;
.LBB0_1061:
	s_movk_i32 s20, 0x57f
	v_cmp_lt_i32_e32 vcc, s20, v0
	s_movk_i32 s20, 0xff00
	s_or_b64 s[24:25], s[38:39], vcc
	v_cndmask_b32_e32 v2, 0, v211, vcc
	v_add_u32_e32 v2, v2, v0
	v_lshlrev_b32_e32 v46, 2, v2
	v_and_b32_e32 v3, 0x7c, v46
	v_lshlrev_b32_e32 v2, 3, v2
	v_and_or_b32 v14, v2, s20, v3
	v_mov_b32_e32 v2, s6
	v_mov_b32_e32 v3, s8
	v_cndmask_b32_e32 v4, v2, v3, vcc
	v_mov_b64_e32 v[2:3], s[94:95]
	v_mad_i64_i32 v[2:3], s[20:21], v4, s3, v[2:3]
	v_ashrrev_i32_e32 v15, 31, v14
	v_lshl_add_u64 v[6:7], v[14:15], 2, v[2:3]
	v_mov_b32_e32 v86, 0
	v_mov_b32_e32 v87, 0
	v_mov_b32_e32 v88, 0
	v_mov_b32_e32 v89, 0
	v_mov_b32_e32 v90, 0
	v_mov_b32_e32 v91, 0
	v_mov_b32_e32 v92, 0
	v_mov_b32_e32 v93, 0
	s_and_saveexec_b64 s[44:45], s[24:25]
	global_load_dwordx4 v[86:89], v[6:7], off
	global_load_dwordx4 v[90:93], v[6:7], off offset:512
	s_or_b64 exec, exec, s[44:45]
	v_mov_b32_e32 v6, s5
	v_mov_b32_e32 v7, s9
	v_cndmask_b32_e32 v6, v6, v7, vcc
	v_mov_b64_e32 v[16:17], s[94:95]
	v_mad_i64_i32 v[6:7], s[20:21], v6, s3, v[16:17]
	v_lshl_add_u64 v[10:11], v[14:15], 2, v[6:7]
	global_load_dwordx4 v[6:9], v[10:11], off
	s_nop 0
	global_load_dwordx4 v[10:13], v[10:11], off offset:512
	v_mov_b32_e32 v18, s7
	v_mov_b32_e32 v19, s10
	s_and_b64 s[20:21], s[40:41], vcc
	v_cndmask_b32_e32 v18, v18, v19, vcc
	s_xor_b64 s[24:25], s[20:21], -1
	v_mad_i64_i32 v[16:17], s[20:21], v18, s3, v[16:17]
	v_lshl_add_u64 v[18:19], v[14:15], 2, v[16:17]
	v_mov_b32_e32 v94, 0
	v_mov_b32_e32 v95, 0
	v_mov_b32_e32 v96, 0
	v_mov_b32_e32 v97, 0
	v_mov_b32_e32 v74, 0
	v_mov_b32_e32 v75, 0
	v_mov_b32_e32 v76, 0
	v_mov_b32_e32 v77, 0
	s_and_saveexec_b64 s[44:45], s[24:25]
	global_load_dwordx4 v[94:97], v[18:19], off
	global_load_dwordx4 v[74:77], v[18:19], off offset:512
	s_or_b64 exec, exec, s[44:45]
	s_waitcnt vmcnt(0)
	v_mov_b32_e32 v53, v86
	v_mov_b32_e32 v3, v87
	v_mov_b32_e32 v49, v88
	v_mov_b32_e32 v5, v89
	v_mov_b32_e32 v52, v90
	v_mov_b32_e32 v2, v91
	v_mov_b32_e32 v48, v92
	v_mov_b32_e32 v4, v93
	v_mov_b32_e32 v55, v94
	v_mov_b32_e32 v15, v95
	v_mov_b32_e32 v51, v96
	v_mov_b32_e32 v17, v97
	v_mov_b32_e32 v54, v74
	v_mov_b32_e32 v14, v75
	v_mov_b32_e32 v50, v76
	v_mov_b32_e32 v16, v77
	s_branch .LBB0_1060
